# NSA-window/SWA unmasked tiles: K fragments shared by both column blocks (no re-read), both QK MFMA groups up front, the two softmax streams interleaved; second block's temporaries in spare VGPRs
# baseline (speedup 1.0000x reference)
.Lsw_p1:
	v_lshl_add_u32 v114, s82, 2, v145
	ds_read2_b32 v[82:83], v114 offset0:127 offset1:128
	ds_read2_b32 v[84:85], v114 offset0:129 offset1:130
	ds_read2_b32 v[86:87], v114 offset0:143 offset1:144
	ds_read2_b32 v[88:89], v114 offset0:145 offset1:146
	s_waitcnt lgkmcnt(4)
	s_setprio 1
	v_mfma_f32_16x16x32_bf16 v[98:101], v[70:73], v[10:13], 0
	v_mfma_f32_16x16x32_bf16 v[102:105], v[74:77], v[10:13], 0
	v_mfma_f32_16x16x32_bf16 v[106:109], v[62:65], v[10:13], 0
	v_mfma_f32_16x16x32_bf16 v[110:113], v[54:57], v[10:13], 0
	ds_read2_b32 v[90:91], v114 offset0:159 offset1:160
	ds_read2_b32 v[92:93], v114 offset0:161 offset1:162
	ds_read2_b32 v[94:95], v114 offset0:175 offset1:176
	ds_read2_b32 v[96:97], v114 offset0:177 offset1:178
	v_mfma_f32_16x16x32_bf16 v[98:101], v[78:81], v[14:17], v[98:101]
	v_mfma_f32_16x16x32_bf16 v[102:105], v[66:69], v[14:17], v[102:105]
	v_mfma_f32_16x16x32_bf16 v[106:109], v[58:61], v[14:17], v[106:109]
	v_mfma_f32_16x16x32_bf16 v[110:113], v[50:53], v[14:17], v[110:113]
	v_mfma_f32_16x16x32_bf16 v[70:73], v[70:73], v[2:5], 0
	v_mfma_f32_16x16x32_bf16 v[74:77], v[74:77], v[2:5], 0
	v_mfma_f32_16x16x32_bf16 v[62:65], v[62:65], v[2:5], 0
	v_mfma_f32_16x16x32_bf16 v[54:57], v[54:57], v[2:5], 0
	v_mfma_f32_16x16x32_bf16 v[70:73], v[78:81], v[6:9], v[70:73]
	v_mfma_f32_16x16x32_bf16 v[74:77], v[66:69], v[6:9], v[74:77]
	v_mfma_f32_16x16x32_bf16 v[62:65], v[58:61], v[6:9], v[62:65]
	v_mfma_f32_16x16x32_bf16 v[54:57], v[50:53], v[6:9], v[54:57]
	s_setprio 0
	s_waitcnt lgkmcnt(0)
	ds_read2_b32 v[78:79], v114 offset0:111 offset1:112
	ds_read2_b32 v[80:81], v114 offset0:113 offset1:114
	ds_read2_b32 v[66:67], v114 offset0:127 offset1:128
	ds_read2_b32 v[68:69], v114 offset0:129 offset1:130
	ds_read2_b32 v[58:59], v114 offset0:143 offset1:144
	ds_read2_b32 v[60:61], v114 offset0:145 offset1:146
	ds_read2_b32 v[50:51], v114 offset0:159 offset1:160
	ds_read2_b32 v[52:53], v114 offset0:161 offset1:162
	v_pk_fma_f32 v[70:71], v[70:71], s[36:37], v[82:83] op_sel_hi:[1,0,1]
	v_pk_fma_f32 v[72:73], v[72:73], s[36:37], v[84:85] op_sel_hi:[1,0,1]
	v_pk_fma_f32 v[74:75], v[74:75], s[36:37], v[86:87] op_sel_hi:[1,0,1]
	v_pk_fma_f32 v[76:77], v[76:77], s[36:37], v[88:89] op_sel_hi:[1,0,1]
	v_pk_fma_f32 v[62:63], v[62:63], s[36:37], v[90:91] op_sel_hi:[1,0,1]
	v_pk_fma_f32 v[64:65], v[64:65], s[36:37], v[92:93] op_sel_hi:[1,0,1]
	v_pk_fma_f32 v[54:55], v[54:55], s[36:37], v[94:95] op_sel_hi:[1,0,1]
	v_pk_fma_f32 v[56:57], v[56:57], s[36:37], v[96:97] op_sel_hi:[1,0,1]
	s_waitcnt lgkmcnt(0)
	v_pk_fma_f32 v[98:99], v[98:99], s[36:37], v[78:79] op_sel_hi:[1,0,1]
	v_pk_fma_f32 v[100:101], v[100:101], s[36:37], v[80:81] op_sel_hi:[1,0,1]
	v_pk_fma_f32 v[102:103], v[102:103], s[36:37], v[66:67] op_sel_hi:[1,0,1]
	v_pk_fma_f32 v[104:105], v[104:105], s[36:37], v[68:69] op_sel_hi:[1,0,1]
	v_pk_fma_f32 v[106:107], v[106:107], s[36:37], v[58:59] op_sel_hi:[1,0,1]
	v_pk_fma_f32 v[108:109], v[108:109], s[36:37], v[60:61] op_sel_hi:[1,0,1]
	v_pk_fma_f32 v[110:111], v[110:111], s[36:37], v[50:51] op_sel_hi:[1,0,1]
	v_pk_fma_f32 v[112:113], v[112:113], s[36:37], v[52:53] op_sel_hi:[1,0,1]
	v_max3_f32 v116, v70, v71, v72
	v_max3_f32 v169, v98, v99, v100
	v_max3_f32 v116, v116, v73, v74
	v_max3_f32 v169, v169, v101, v102
	v_max3_f32 v116, v116, v75, v76
	v_max3_f32 v169, v169, v103, v104
	v_max3_f32 v116, v116, v77, v62
	v_max3_f32 v169, v169, v105, v106
	v_max3_f32 v116, v116, v63, v64
	v_max3_f32 v169, v169, v107, v108
	v_max3_f32 v116, v116, v65, v54
	v_max3_f32 v169, v169, v109, v110
	v_max3_f32 v116, v116, v55, v56
	v_max3_f32 v169, v169, v111, v112
	v_max3_f32 v116, v116, v57, s29
	v_max3_f32 v169, v169, v113, s29
	v_mov_b32_e32 v117, v116
	v_mov_b32_e32 v170, v169
	s_nop 1
	s_nop 1
	v_permlane16_swap_b32_e32 v116, v117
	v_permlane16_swap_b32_e32 v169, v170
	v_max_f32_e32 v116, v116, v117
	v_max_f32_e32 v169, v169, v170
	v_mov_b32_e32 v117, v116
	v_mov_b32_e32 v170, v169
	s_nop 1
	s_nop 1
	v_permlane32_swap_b32_e32 v116, v117
	v_permlane32_swap_b32_e32 v169, v170
	v_max_f32_e32 v116, v116, v117
	v_max_f32_e32 v169, v169, v170
	v_max_f32_e32 v121, v166, v116
	v_max_f32_e32 v175, v167, v169
	v_sub_f32_e32 v118, v166, v121
	v_sub_f32_e32 v172, v167, v175
	v_exp_f32_e32 v118, v118
	v_exp_f32_e32 v172, v172
	v_mov_b32_e32 v166, v121
	v_mov_b32_e32 v167, v175
	v_mov_b32_e32 v120, v121
	v_mov_b32_e32 v174, v175
	v_pk_mul_f32 v[46:47], v[46:47], v[118:119] op_sel_hi:[1,0]
	v_pk_mul_f32 v[30:31], v[30:31], v[172:173] op_sel_hi:[1,0]
	v_pk_mul_f32 v[48:49], v[48:49], v[118:119] op_sel_hi:[1,0]
	v_pk_mul_f32 v[32:33], v[32:33], v[172:173] op_sel_hi:[1,0]
	v_pk_mul_f32 v[42:43], v[42:43], v[118:119] op_sel_hi:[1,0]
	v_pk_mul_f32 v[26:27], v[26:27], v[172:173] op_sel_hi:[1,0]
	v_pk_mul_f32 v[44:45], v[44:45], v[118:119] op_sel_hi:[1,0]
	v_pk_mul_f32 v[28:29], v[28:29], v[172:173] op_sel_hi:[1,0]
	v_pk_mul_f32 v[38:39], v[38:39], v[118:119] op_sel_hi:[1,0]
	v_pk_mul_f32 v[22:23], v[22:23], v[172:173] op_sel_hi:[1,0]
	v_pk_mul_f32 v[40:41], v[40:41], v[118:119] op_sel_hi:[1,0]
	v_pk_mul_f32 v[24:25], v[24:25], v[172:173] op_sel_hi:[1,0]
	v_pk_mul_f32 v[34:35], v[34:35], v[118:119] op_sel_hi:[1,0]
	v_pk_mul_f32 v[18:19], v[18:19], v[172:173] op_sel_hi:[1,0]
	v_pk_mul_f32 v[36:37], v[36:37], v[118:119] op_sel_hi:[1,0]
	v_pk_mul_f32 v[20:21], v[20:21], v[172:173] op_sel_hi:[1,0]
	v_pk_add_f32 v[70:71], v[70:71], v[120:121] op_sel_hi:[1,0] neg_lo:[0,1] neg_hi:[0,1]
	v_pk_add_f32 v[98:99], v[98:99], v[174:175] op_sel_hi:[1,0] neg_lo:[0,1] neg_hi:[0,1]
	v_pk_add_f32 v[72:73], v[72:73], v[120:121] op_sel_hi:[1,0] neg_lo:[0,1] neg_hi:[0,1]
	v_pk_add_f32 v[100:101], v[100:101], v[174:175] op_sel_hi:[1,0] neg_lo:[0,1] neg_hi:[0,1]
	v_pk_add_f32 v[74:75], v[74:75], v[120:121] op_sel_hi:[1,0] neg_lo:[0,1] neg_hi:[0,1]
	v_pk_add_f32 v[102:103], v[102:103], v[174:175] op_sel_hi:[1,0] neg_lo:[0,1] neg_hi:[0,1]
	v_pk_add_f32 v[76:77], v[76:77], v[120:121] op_sel_hi:[1,0] neg_lo:[0,1] neg_hi:[0,1]
	v_pk_add_f32 v[104:105], v[104:105], v[174:175] op_sel_hi:[1,0] neg_lo:[0,1] neg_hi:[0,1]
	v_pk_add_f32 v[62:63], v[62:63], v[120:121] op_sel_hi:[1,0] neg_lo:[0,1] neg_hi:[0,1]
	v_pk_add_f32 v[106:107], v[106:107], v[174:175] op_sel_hi:[1,0] neg_lo:[0,1] neg_hi:[0,1]
	v_pk_add_f32 v[64:65], v[64:65], v[120:121] op_sel_hi:[1,0] neg_lo:[0,1] neg_hi:[0,1]
	v_pk_add_f32 v[108:109], v[108:109], v[174:175] op_sel_hi:[1,0] neg_lo:[0,1] neg_hi:[0,1]
	v_pk_add_f32 v[54:55], v[54:55], v[120:121] op_sel_hi:[1,0] neg_lo:[0,1] neg_hi:[0,1]
	v_pk_add_f32 v[110:111], v[110:111], v[174:175] op_sel_hi:[1,0] neg_lo:[0,1] neg_hi:[0,1]
	v_pk_add_f32 v[56:57], v[56:57], v[120:121] op_sel_hi:[1,0] neg_lo:[0,1] neg_hi:[0,1]
	v_pk_add_f32 v[112:113], v[112:113], v[174:175] op_sel_hi:[1,0] neg_lo:[0,1] neg_hi:[0,1]
	v_exp_f32_e32 v70, v70
	v_exp_f32_e32 v98, v98
	v_exp_f32_e32 v71, v71
	v_exp_f32_e32 v99, v99
	v_exp_f32_e32 v72, v72
	v_exp_f32_e32 v100, v100
	v_exp_f32_e32 v73, v73
	v_exp_f32_e32 v101, v101
	v_exp_f32_e32 v74, v74
	v_exp_f32_e32 v102, v102
	v_exp_f32_e32 v75, v75
	v_exp_f32_e32 v103, v103
	v_exp_f32_e32 v76, v76
	v_exp_f32_e32 v104, v104
	v_exp_f32_e32 v77, v77
	v_exp_f32_e32 v105, v105
	v_exp_f32_e32 v62, v62
	v_exp_f32_e32 v106, v106
	v_exp_f32_e32 v63, v63
	v_exp_f32_e32 v107, v107
	v_exp_f32_e32 v64, v64
	v_exp_f32_e32 v108, v108
	v_exp_f32_e32 v65, v65
	v_exp_f32_e32 v109, v109
	v_exp_f32_e32 v54, v54
	v_exp_f32_e32 v110, v110
	v_exp_f32_e32 v55, v55
	v_exp_f32_e32 v111, v111
	v_exp_f32_e32 v56, v56
	v_exp_f32_e32 v112, v112
	v_exp_f32_e32 v57, v57
	v_exp_f32_e32 v113, v113
	s_nop 0
	s_nop 0
	v_pk_add_f32 v[82:83], v[70:71], v[72:73]
	v_pk_add_f32 v[78:79], v[98:99], v[100:101]
	v_pk_add_f32 v[84:85], v[74:75], v[76:77]
	v_pk_add_f32 v[80:81], v[102:103], v[104:105]
	v_pk_add_f32 v[86:87], v[62:63], v[64:65]
	v_pk_add_f32 v[66:67], v[106:107], v[108:109]
	v_pk_add_f32 v[88:89], v[54:55], v[56:57]
	v_pk_add_f32 v[68:69], v[110:111], v[112:113]
	v_pk_add_f32 v[82:83], v[82:83], v[84:85]
	v_pk_add_f32 v[78:79], v[78:79], v[80:81]
	v_pk_add_f32 v[86:87], v[86:87], v[88:89]
	v_pk_add_f32 v[66:67], v[66:67], v[68:69]
	s_nop 0
	s_nop 0
	v_pk_add_f32 v[82:83], v[82:83], v[86:87]
	v_pk_add_f32 v[78:79], v[78:79], v[66:67]
	s_nop 0
	s_nop 0
	v_add_f32_e32 v82, v82, v83
	v_add_f32_e32 v78, v78, v79
	v_fma_f32 v158, v158, v118, v82
	v_fma_f32 v159, v159, v172, v78
	v_cvt_pk_bf16_f32 v77, v76, v77
	v_cvt_pk_bf16_f32 v105, v104, v105
	v_cvt_pk_bf16_f32 v76, v74, v75
	v_cvt_pk_bf16_f32 v104, v102, v103
	v_cvt_pk_bf16_f32 v75, v72, v73
	v_cvt_pk_bf16_f32 v103, v100, v101
	v_cvt_pk_bf16_f32 v74, v70, v71
	v_cvt_pk_bf16_f32 v102, v98, v99
	v_cvt_pk_bf16_f32 v62, v62, v63
	v_cvt_pk_bf16_f32 v106, v106, v107
	v_cvt_pk_bf16_f32 v63, v64, v65
	v_cvt_pk_bf16_f32 v107, v108, v109
	v_cvt_pk_bf16_f32 v64, v54, v55
	v_cvt_pk_bf16_f32 v108, v110, v111
	v_cvt_pk_bf16_f32 v65, v56, v57
	v_cvt_pk_bf16_f32 v109, v112, v113

.Lnw_p1:
	v_lshl_add_u32 v114, s25, 2, v145
	v_add_u32_e32 v115, 0xffc, v114
	v_add_u32_e32 v168, 0xfbc, v114
	ds_read2_b32 v[82:83], v115 offset1:1
	ds_read2_b32 v[84:85], v115 offset0:2 offset1:3
	ds_read2_b32 v[86:87], v115 offset0:16 offset1:17
	ds_read2_b32 v[88:89], v115 offset0:18 offset1:19
	s_waitcnt lgkmcnt(4)
	s_setprio 1
	v_mfma_f32_16x16x32_bf16 v[98:101], v[78:81], v[10:13], 0
	v_mfma_f32_16x16x32_bf16 v[102:105], v[70:73], v[10:13], 0
	v_mfma_f32_16x16x32_bf16 v[106:109], v[62:65], v[10:13], 0
	v_mfma_f32_16x16x32_bf16 v[110:113], v[54:57], v[10:13], 0
	ds_read2_b32 v[90:91], v115 offset0:32 offset1:33
	ds_read2_b32 v[92:93], v115 offset0:34 offset1:35
	ds_read2_b32 v[94:95], v115 offset0:48 offset1:49
	ds_read2_b32 v[96:97], v115 offset0:50 offset1:51
	v_mfma_f32_16x16x32_bf16 v[98:101], v[74:77], v[14:17], v[98:101]
	v_mfma_f32_16x16x32_bf16 v[102:105], v[66:69], v[14:17], v[102:105]
	v_mfma_f32_16x16x32_bf16 v[106:109], v[58:61], v[14:17], v[106:109]
	v_mfma_f32_16x16x32_bf16 v[110:113], v[50:53], v[14:17], v[110:113]
	v_mfma_f32_16x16x32_bf16 v[78:81], v[78:81], v[2:5], 0
	v_mfma_f32_16x16x32_bf16 v[70:73], v[70:73], v[2:5], 0
	v_mfma_f32_16x16x32_bf16 v[62:65], v[62:65], v[2:5], 0
	v_mfma_f32_16x16x32_bf16 v[54:57], v[54:57], v[2:5], 0
	v_mfma_f32_16x16x32_bf16 v[78:81], v[74:77], v[6:9], v[78:81]
	v_mfma_f32_16x16x32_bf16 v[70:73], v[66:69], v[6:9], v[70:73]
	v_mfma_f32_16x16x32_bf16 v[62:65], v[58:61], v[6:9], v[62:65]
	v_mfma_f32_16x16x32_bf16 v[54:57], v[50:53], v[6:9], v[54:57]
	s_setprio 0
	s_waitcnt lgkmcnt(0)
	ds_read2_b32 v[74:75], v168 offset1:1
	ds_read2_b32 v[76:77], v168 offset0:2 offset1:3
	ds_read2_b32 v[66:67], v168 offset0:16 offset1:17
	ds_read2_b32 v[68:69], v168 offset0:18 offset1:19
	ds_read2_b32 v[58:59], v168 offset0:32 offset1:33
	ds_read2_b32 v[60:61], v168 offset0:34 offset1:35
	ds_read2_b32 v[50:51], v168 offset0:48 offset1:49
	ds_read2_b32 v[52:53], v168 offset0:50 offset1:51
	v_pk_fma_f32 v[78:79], v[78:79], s[36:37], v[82:83] op_sel_hi:[1,0,1]
	v_pk_fma_f32 v[80:81], v[80:81], s[36:37], v[84:85] op_sel_hi:[1,0,1]
	v_pk_fma_f32 v[70:71], v[70:71], s[36:37], v[86:87] op_sel_hi:[1,0,1]
	v_pk_fma_f32 v[72:73], v[72:73], s[36:37], v[88:89] op_sel_hi:[1,0,1]
	v_pk_fma_f32 v[62:63], v[62:63], s[36:37], v[90:91] op_sel_hi:[1,0,1]
	v_pk_fma_f32 v[64:65], v[64:65], s[36:37], v[92:93] op_sel_hi:[1,0,1]
	v_pk_fma_f32 v[54:55], v[54:55], s[36:37], v[94:95] op_sel_hi:[1,0,1]
	v_pk_fma_f32 v[56:57], v[56:57], s[36:37], v[96:97] op_sel_hi:[1,0,1]
	s_waitcnt lgkmcnt(0)
	v_pk_fma_f32 v[98:99], v[98:99], s[36:37], v[74:75] op_sel_hi:[1,0,1]
	v_pk_fma_f32 v[100:101], v[100:101], s[36:37], v[76:77] op_sel_hi:[1,0,1]
	v_pk_fma_f32 v[102:103], v[102:103], s[36:37], v[66:67] op_sel_hi:[1,0,1]
	v_pk_fma_f32 v[104:105], v[104:105], s[36:37], v[68:69] op_sel_hi:[1,0,1]
	v_pk_fma_f32 v[106:107], v[106:107], s[36:37], v[58:59] op_sel_hi:[1,0,1]
	v_pk_fma_f32 v[108:109], v[108:109], s[36:37], v[60:61] op_sel_hi:[1,0,1]
	v_pk_fma_f32 v[110:111], v[110:111], s[36:37], v[50:51] op_sel_hi:[1,0,1]
	v_pk_fma_f32 v[112:113], v[112:113], s[36:37], v[52:53] op_sel_hi:[1,0,1]
	v_max3_f32 v116, v78, v79, v80
	v_max3_f32 v169, v98, v99, v100
	v_max3_f32 v116, v116, v81, v70
	v_max3_f32 v169, v169, v101, v102
	v_max3_f32 v116, v116, v71, v72
	v_max3_f32 v169, v169, v103, v104
	v_max3_f32 v116, v116, v73, v62
	v_max3_f32 v169, v169, v105, v106
	v_max3_f32 v116, v116, v63, v64
	v_max3_f32 v169, v169, v107, v108
	v_max3_f32 v116, v116, v65, v54
	v_max3_f32 v169, v169, v109, v110
	v_max3_f32 v116, v116, v55, v56
	v_max3_f32 v169, v169, v111, v112
	v_max3_f32 v116, v116, v57, s29
	v_max3_f32 v169, v169, v113, s29
	v_mov_b32_e32 v117, v116
	v_mov_b32_e32 v170, v169
	s_nop 1
	s_nop 1
	v_permlane16_swap_b32_e32 v116, v117
	v_permlane16_swap_b32_e32 v169, v170
	v_max_f32_e32 v116, v116, v117
	v_max_f32_e32 v169, v169, v170
	v_mov_b32_e32 v117, v116
	v_mov_b32_e32 v170, v169
	s_nop 1
	s_nop 1
	v_permlane32_swap_b32_e32 v116, v117
	v_permlane32_swap_b32_e32 v169, v170
	v_max_f32_e32 v116, v116, v117
	v_max_f32_e32 v169, v169, v170
	v_max_f32_e32 v121, v166, v116
	v_max_f32_e32 v175, v167, v169
	v_sub_f32_e32 v118, v166, v121
	v_sub_f32_e32 v172, v167, v175
	v_exp_f32_e32 v118, v118
	v_exp_f32_e32 v172, v172
	v_mov_b32_e32 v166, v121
	v_mov_b32_e32 v167, v175
	v_mov_b32_e32 v120, v121
	v_mov_b32_e32 v174, v175
	v_pk_mul_f32 v[46:47], v[46:47], v[118:119] op_sel_hi:[1,0]
	v_pk_mul_f32 v[30:31], v[30:31], v[172:173] op_sel_hi:[1,0]
	v_pk_mul_f32 v[48:49], v[48:49], v[118:119] op_sel_hi:[1,0]
	v_pk_mul_f32 v[32:33], v[32:33], v[172:173] op_sel_hi:[1,0]
	v_pk_mul_f32 v[42:43], v[42:43], v[118:119] op_sel_hi:[1,0]
	v_pk_mul_f32 v[26:27], v[26:27], v[172:173] op_sel_hi:[1,0]
	v_pk_mul_f32 v[44:45], v[44:45], v[118:119] op_sel_hi:[1,0]
	v_pk_mul_f32 v[28:29], v[28:29], v[172:173] op_sel_hi:[1,0]
	v_pk_mul_f32 v[38:39], v[38:39], v[118:119] op_sel_hi:[1,0]
	v_pk_mul_f32 v[22:23], v[22:23], v[172:173] op_sel_hi:[1,0]
	v_pk_mul_f32 v[40:41], v[40:41], v[118:119] op_sel_hi:[1,0]
	v_pk_mul_f32 v[24:25], v[24:25], v[172:173] op_sel_hi:[1,0]
	v_pk_mul_f32 v[34:35], v[34:35], v[118:119] op_sel_hi:[1,0]
	v_pk_mul_f32 v[18:19], v[18:19], v[172:173] op_sel_hi:[1,0]
	v_pk_mul_f32 v[36:37], v[36:37], v[118:119] op_sel_hi:[1,0]
	v_pk_mul_f32 v[20:21], v[20:21], v[172:173] op_sel_hi:[1,0]
	v_pk_add_f32 v[78:79], v[78:79], v[120:121] op_sel_hi:[1,0] neg_lo:[0,1] neg_hi:[0,1]
	v_pk_add_f32 v[98:99], v[98:99], v[174:175] op_sel_hi:[1,0] neg_lo:[0,1] neg_hi:[0,1]
	v_pk_add_f32 v[80:81], v[80:81], v[120:121] op_sel_hi:[1,0] neg_lo:[0,1] neg_hi:[0,1]
	v_pk_add_f32 v[100:101], v[100:101], v[174:175] op_sel_hi:[1,0] neg_lo:[0,1] neg_hi:[0,1]
	v_pk_add_f32 v[70:71], v[70:71], v[120:121] op_sel_hi:[1,0] neg_lo:[0,1] neg_hi:[0,1]
	v_pk_add_f32 v[102:103], v[102:103], v[174:175] op_sel_hi:[1,0] neg_lo:[0,1] neg_hi:[0,1]
	v_pk_add_f32 v[72:73], v[72:73], v[120:121] op_sel_hi:[1,0] neg_lo:[0,1] neg_hi:[0,1]
	v_pk_add_f32 v[104:105], v[104:105], v[174:175] op_sel_hi:[1,0] neg_lo:[0,1] neg_hi:[0,1]
	v_pk_add_f32 v[62:63], v[62:63], v[120:121] op_sel_hi:[1,0] neg_lo:[0,1] neg_hi:[0,1]
	v_pk_add_f32 v[106:107], v[106:107], v[174:175] op_sel_hi:[1,0] neg_lo:[0,1] neg_hi:[0,1]
	v_pk_add_f32 v[64:65], v[64:65], v[120:121] op_sel_hi:[1,0] neg_lo:[0,1] neg_hi:[0,1]
	v_pk_add_f32 v[108:109], v[108:109], v[174:175] op_sel_hi:[1,0] neg_lo:[0,1] neg_hi:[0,1]
	v_pk_add_f32 v[54:55], v[54:55], v[120:121] op_sel_hi:[1,0] neg_lo:[0,1] neg_hi:[0,1]
	v_pk_add_f32 v[110:111], v[110:111], v[174:175] op_sel_hi:[1,0] neg_lo:[0,1] neg_hi:[0,1]
	v_pk_add_f32 v[56:57], v[56:57], v[120:121] op_sel_hi:[1,0] neg_lo:[0,1] neg_hi:[0,1]
	v_pk_add_f32 v[112:113], v[112:113], v[174:175] op_sel_hi:[1,0] neg_lo:[0,1] neg_hi:[0,1]
	v_exp_f32_e32 v78, v78
	v_exp_f32_e32 v98, v98
	v_exp_f32_e32 v79, v79
	v_exp_f32_e32 v99, v99
	v_exp_f32_e32 v80, v80
	v_exp_f32_e32 v100, v100
	v_exp_f32_e32 v81, v81
	v_exp_f32_e32 v101, v101
	v_exp_f32_e32 v70, v70
	v_exp_f32_e32 v102, v102
	v_exp_f32_e32 v71, v71
	v_exp_f32_e32 v103, v103
	v_exp_f32_e32 v72, v72
	v_exp_f32_e32 v104, v104
	v_exp_f32_e32 v73, v73
	v_exp_f32_e32 v105, v105
	v_exp_f32_e32 v62, v62
	v_exp_f32_e32 v106, v106
	v_exp_f32_e32 v63, v63
	v_exp_f32_e32 v107, v107
	v_exp_f32_e32 v64, v64
	v_exp_f32_e32 v108, v108
	v_exp_f32_e32 v65, v65
	v_exp_f32_e32 v109, v109
	v_exp_f32_e32 v54, v54
	v_exp_f32_e32 v110, v110
	v_exp_f32_e32 v55, v55
	v_exp_f32_e32 v111, v111
	v_exp_f32_e32 v56, v56
	v_exp_f32_e32 v112, v112
	v_exp_f32_e32 v57, v57
	v_exp_f32_e32 v113, v113
	s_nop 0
	s_nop 0
	v_pk_add_f32 v[82:83], v[78:79], v[80:81]
	v_pk_add_f32 v[74:75], v[98:99], v[100:101]
	v_pk_add_f32 v[84:85], v[70:71], v[72:73]
	v_pk_add_f32 v[76:77], v[102:103], v[104:105]
	v_pk_add_f32 v[86:87], v[62:63], v[64:65]
	v_pk_add_f32 v[66:67], v[106:107], v[108:109]
	v_pk_add_f32 v[88:89], v[54:55], v[56:57]
	v_pk_add_f32 v[68:69], v[110:111], v[112:113]
	v_pk_add_f32 v[82:83], v[82:83], v[84:85]
	v_pk_add_f32 v[74:75], v[74:75], v[76:77]
	v_pk_add_f32 v[86:87], v[86:87], v[88:89]
	v_pk_add_f32 v[66:67], v[66:67], v[68:69]
	s_nop 0
	s_nop 0
	v_pk_add_f32 v[82:83], v[82:83], v[86:87]
	v_pk_add_f32 v[74:75], v[74:75], v[66:67]
	s_nop 0
	s_nop 0
	v_add_f32_e32 v82, v82, v83
	v_add_f32_e32 v74, v74, v75
	v_fma_f32 v160, v160, v118, v82
	v_fma_f32 v161, v161, v172, v74
	v_cvt_pk_bf16_f32 v73, v72, v73
	v_cvt_pk_bf16_f32 v105, v104, v105
	v_cvt_pk_bf16_f32 v72, v70, v71
	v_cvt_pk_bf16_f32 v104, v102, v103
	v_cvt_pk_bf16_f32 v71, v80, v81
	v_cvt_pk_bf16_f32 v103, v100, v101
	v_cvt_pk_bf16_f32 v70, v78, v79
	v_cvt_pk_bf16_f32 v102, v98, v99
	v_cvt_pk_bf16_f32 v62, v62, v63
	v_cvt_pk_bf16_f32 v106, v106, v107
	v_cvt_pk_bf16_f32 v63, v64, v65
	v_cvt_pk_bf16_f32 v107, v108, v109
	v_cvt_pk_bf16_f32 v64, v54, v55
	v_cvt_pk_bf16_f32 v108, v110, v111
	v_cvt_pk_bf16_f32 v65, v56, v57
	v_cvt_pk_bf16_f32 v109, v112, v113
